# stack34 + mLSTM stage C / stage A: the eight V-tile loads issued ahead of the preceding staging phase (Q/K/CT loads, conv loop), later vmcnt waits dropped
# baseline (speedup 1.0000x reference)
.LBB0_519:
	s_or_b64 exec, exec, s[4:5]
	v_cmp_gt_i32_e32 vcc, s48, v2
	s_waitcnt lgkmcnt(0)
	s_barrier
	s_and_saveexec_b64 s[42:43], vcc
	s_cbranch_execz .LBB0_534
	s_lshl_b32 s58, s57, 7
	s_add_i32 s59, s56, -3
	s_mov_b64 s[44:45], 0
	v_mov_b32_e32 v25, v2
	s_lshl_b32 s4, s57, 9
	s_add_u32 s4, s28, s4
	s_addc_u32 s5, s29, 0
	v_and_b32_e32 v216, 0x7f, v2
	v_ashrrev_i32_e32 v217, 7, v2
	v_or_b32_e32 v218, s56, v216
	v_mul_u32_u24_e32 v218, 0x1800, v218
	v_lshl_add_u32 v218, v217, 4, v218
	global_load_dwordx4 v[184:187], v218, s[4:5] offset:2048
	global_load_dwordx4 v[188:191], v218, s[4:5] offset:2112
	global_load_dwordx4 v[192:195], v218, s[4:5] offset:2176
	global_load_dwordx4 v[196:199], v218, s[4:5] offset:2240
	global_load_dwordx4 v[200:203], v218, s[4:5] offset:2304
	global_load_dwordx4 v[204:207], v218, s[4:5] offset:2368
	global_load_dwordx4 v[208:211], v218, s[4:5] offset:2432
	global_load_dwordx4 v[212:215], v218, s[4:5] offset:2496
	s_branch .LBB0_522

.LBB0_532:
	s_or_b64 exec, exec, s[44:45]
	v_mul_u32_u24_e32 v217, 0x880, v217
	v_lshl_add_u32 v217, v216, 1, v217
	v_add_u32_e32 v217, 0x9800, v217
	ds_write_b16 v217, v184 offset:0
	ds_write_b16_d16_hi v217, v184 offset:272
	ds_write_b16 v217, v185 offset:544
	ds_write_b16_d16_hi v217, v185 offset:816
	ds_write_b16 v217, v186 offset:1088
	ds_write_b16_d16_hi v217, v186 offset:1360
	ds_write_b16 v217, v187 offset:1632
	ds_write_b16_d16_hi v217, v187 offset:1904
	ds_write_b16 v217, v188 offset:8704
	ds_write_b16_d16_hi v217, v188 offset:8976
	ds_write_b16 v217, v189 offset:9248
	ds_write_b16_d16_hi v217, v189 offset:9520
	ds_write_b16 v217, v190 offset:9792
	ds_write_b16_d16_hi v217, v190 offset:10064
	ds_write_b16 v217, v191 offset:10336
	ds_write_b16_d16_hi v217, v191 offset:10608
	ds_write_b16 v217, v192 offset:17408
	ds_write_b16_d16_hi v217, v192 offset:17680
	ds_write_b16 v217, v193 offset:17952
	ds_write_b16_d16_hi v217, v193 offset:18224
	ds_write_b16 v217, v194 offset:18496
	ds_write_b16_d16_hi v217, v194 offset:18768
	ds_write_b16 v217, v195 offset:19040
	ds_write_b16_d16_hi v217, v195 offset:19312
	ds_write_b16 v217, v196 offset:26112
	ds_write_b16_d16_hi v217, v196 offset:26384
	ds_write_b16 v217, v197 offset:26656
	ds_write_b16_d16_hi v217, v197 offset:26928
	ds_write_b16 v217, v198 offset:27200
	ds_write_b16_d16_hi v217, v198 offset:27472
	ds_write_b16 v217, v199 offset:27744
	ds_write_b16_d16_hi v217, v199 offset:28016
	ds_write_b16 v217, v200 offset:34816
	ds_write_b16_d16_hi v217, v200 offset:35088
	ds_write_b16 v217, v201 offset:35360
	ds_write_b16_d16_hi v217, v201 offset:35632
	ds_write_b16 v217, v202 offset:35904
	ds_write_b16_d16_hi v217, v202 offset:36176
	ds_write_b16 v217, v203 offset:36448
	ds_write_b16_d16_hi v217, v203 offset:36720
	ds_write_b16 v217, v204 offset:43520
	ds_write_b16_d16_hi v217, v204 offset:43792
	ds_write_b16 v217, v205 offset:44064
	ds_write_b16_d16_hi v217, v205 offset:44336
	ds_write_b16 v217, v206 offset:44608
	ds_write_b16_d16_hi v217, v206 offset:44880
	ds_write_b16 v217, v207 offset:45152
	ds_write_b16_d16_hi v217, v207 offset:45424
	ds_write_b16 v217, v208 offset:52224
	ds_write_b16_d16_hi v217, v208 offset:52496
	ds_write_b16 v217, v209 offset:52768
	ds_write_b16_d16_hi v217, v209 offset:53040
	ds_write_b16 v217, v210 offset:53312
	ds_write_b16_d16_hi v217, v210 offset:53584
	ds_write_b16 v217, v211 offset:53856
	ds_write_b16_d16_hi v217, v211 offset:54128
	ds_write_b16 v217, v212 offset:60928
	ds_write_b16_d16_hi v217, v212 offset:61200
	ds_write_b16 v217, v213 offset:61472
	ds_write_b16_d16_hi v217, v213 offset:61744
	ds_write_b16 v217, v214 offset:62016
	ds_write_b16_d16_hi v217, v214 offset:62288
	ds_write_b16 v217, v215 offset:62560
	ds_write_b16_d16_hi v217, v215 offset:62832

.LBB0_923:
	s_or_b64 exec, exec, s[4:5]
	s_lshl_b32 s6, s16, 9
	s_add_u32 s6, s30, s6
	s_addc_u32 s7, s31, 0
	v_and_b32_e32 v212, 0x7f, v78
	v_ashrrev_i32_e32 v213, 7, v78
	v_or_b32_e32 v214, s91, v212
	v_mul_lo_u32 v214, v214, s88
	v_lshl_add_u32 v214, v213, 4, v214
	global_load_dwordx4 v[180:183], v214, s[6:7] offset:2048
	global_load_dwordx4 v[184:187], v214, s[6:7] offset:2112
	global_load_dwordx4 v[188:191], v214, s[6:7] offset:2176
	global_load_dwordx4 v[192:195], v214, s[6:7] offset:2240
	global_load_dwordx4 v[196:199], v214, s[6:7] offset:2304
	global_load_dwordx4 v[200:203], v214, s[6:7] offset:2368
	global_load_dwordx4 v[204:207], v214, s[6:7] offset:2432
	global_load_dwordx4 v[208:211], v214, s[6:7] offset:2496
	v_and_b32_e32 v92, 15, v88
	v_lshlrev_b32_e32 v76, 4, v92
	v_ashrrev_i32_e32 v64, 4, v78
	s_lshl_b32 s6, s16, 8
	s_add_u32 s4, s63, s6
	s_addc_u32 s5, s64, 0
	s_add_u32 s6, s65, s6
	s_addc_u32 s7, s66, 0
	v_add_u32_e32 v65, s91, v64
	v_lshl_add_u32 v65, v65, 10, v76
	s_ashr_i32 s55, s54, 31
	s_lshl_b64 s[8:9], s[54:55], 16
	s_add_u32 s8, s67, s8
	s_addc_u32 s9, s68, s9
	v_lshl_add_u32 v66, v64, 8, v76
	v_cmp_gt_i32_e64 s[2:3], s83, v78
	global_load_dwordx4 v[0:3], v65, s[4:5]
	global_load_dwordx4 v[4:7], v65, s[6:7]
	s_add_u32 s4, s4, 0x8000
	s_addc_u32 s5, s5, 0
	s_add_u32 s6, s6, 0x8000
	s_addc_u32 s7, s7, 0
	global_load_dwordx4 v[8:11], v65, s[4:5]
	global_load_dwordx4 v[12:15], v65, s[6:7]
	s_add_u32 s4, s4, 0x8000
	s_addc_u32 s5, s5, 0
	s_add_u32 s6, s6, 0x8000
	s_addc_u32 s7, s7, 0
	global_load_dwordx4 v[16:19], v65, s[4:5]
	global_load_dwordx4 v[20:23], v65, s[6:7]
	s_add_u32 s4, s4, 0x8000
	s_addc_u32 s5, s5, 0
	s_add_u32 s6, s6, 0x8000
	s_addc_u32 s7, s7, 0
	global_load_dwordx4 v[24:27], v65, s[4:5]
	global_load_dwordx4 v[28:31], v65, s[6:7]
	global_load_dwordx4 v[32:35], v66, s[8:9]
	s_add_u32 s8, s8, 0x2000
	s_addc_u32 s9, s9, 0
	global_load_dwordx4 v[36:39], v66, s[8:9]
	s_add_u32 s8, s8, 0x2000
	s_addc_u32 s9, s9, 0
	global_load_dwordx4 v[40:43], v66, s[8:9]
	s_add_u32 s8, s8, 0x2000
	s_addc_u32 s9, s9, 0
	global_load_dwordx4 v[44:47], v66, s[8:9]
	s_add_u32 s8, s8, 0x2000
	s_addc_u32 s9, s9, 0
	global_load_dwordx4 v[48:51], v66, s[8:9]
	s_add_u32 s8, s8, 0x2000
	s_addc_u32 s9, s9, 0
	global_load_dwordx4 v[52:55], v66, s[8:9]
	s_add_u32 s8, s8, 0x2000
	s_addc_u32 s9, s9, 0
	global_load_dwordx4 v[56:59], v66, s[8:9]
	s_add_u32 s8, s8, 0x2000
	s_addc_u32 s9, s9, 0
	global_load_dwordx4 v[60:63], v66, s[8:9]
	v_mad_u32_u24 v67, v64, s81, v76
	v_add_u32_e32 v68, s84, v67
	s_waitcnt vmcnt(15)
	ds_write_b128 v67, v[0:3] offset:4096
	s_waitcnt vmcnt(14)
	ds_write_b128 v67, v[4:7] offset:38912
	s_waitcnt vmcnt(13)
	ds_write_b128 v67, v[8:11] offset:12800
	s_waitcnt vmcnt(12)
	ds_write_b128 v67, v[12:15] offset:47616
	s_waitcnt vmcnt(11)
	ds_write_b128 v67, v[16:19] offset:21504
	s_waitcnt vmcnt(10)
	ds_write_b128 v67, v[20:23] offset:56320
	s_waitcnt vmcnt(9)
	ds_write_b128 v67, v[24:27] offset:30208
	s_waitcnt vmcnt(8)
	ds_write_b128 v67, v[28:31] offset:65024
	s_waitcnt vmcnt(7)
	ds_write_b128 v68, v[32:35] offset:0
	s_waitcnt vmcnt(6)
	ds_write_b128 v68, v[36:39] offset:8704
	s_waitcnt vmcnt(5)
	ds_write_b128 v68, v[40:43] offset:17408
	s_waitcnt vmcnt(4)
	ds_write_b128 v68, v[44:47] offset:26112
	s_waitcnt vmcnt(3)
	ds_write_b128 v68, v[48:51] offset:34816
	s_waitcnt vmcnt(2)
	ds_write_b128 v68, v[52:55] offset:43520
	s_waitcnt vmcnt(1)
	ds_write_b128 v68, v[56:59] offset:52224
	s_waitcnt vmcnt(0)
	ds_write_b128 v68, v[60:63] offset:60928

.LBB0_946:
	v_add_u32_e32 v94, s75, v89
	v_lshl_add_u32 v76, v92, 2, 0
	ds_read_b128 v[48:51], v94 offset:512
	ds_read2_b32 v[56:57], v76 offset1:16
	v_add_u32_e32 v59, s84, v89
	v_add_u32_e32 v93, v59, v79
	ds_read_b128 v[52:55], v93
	v_lshl_add_u32 v91, v58, 2, s74
	s_waitcnt lgkmcnt(1)
	v_sub_f32_e32 v58, v56, v49
	v_mul_f32_e32 v58, 0x3fb8aa3b, v58
	v_exp_f32_e32 v58, v58
	v_sub_f32_e32 v60, v56, v48
	v_mul_f32_e32 v60, 0x3fb8aa3b, v60
	v_exp_f32_e32 v60, v60
	v_mul_f32_e32 v41, v41, v58
	v_sub_f32_e32 v58, v56, v50
	v_sub_f32_e32 v56, v56, v51
	v_mul_f32_e32 v56, 0x3fb8aa3b, v56
	v_exp_f32_e32 v56, v56
	v_mul_f32_e32 v58, 0x3fb8aa3b, v58
	v_exp_f32_e32 v58, v58
	v_mul_f32_e32 v40, v40, v60
	v_mul_f32_e32 v43, v43, v56
	v_sub_f32_e32 v56, v57, v48
	v_mul_f32_e32 v56, 0x3fb8aa3b, v56
	v_exp_f32_e32 v56, v56
	v_cmp_le_i32_e32 vcc, v92, v91
	v_or_b32_e32 v60, 1, v91
	v_or_b32_e32 v61, 2, v91
	v_mul_f32_e32 v28, v28, v56
	v_sub_f32_e32 v56, v57, v49
	v_mul_f32_e32 v56, 0x3fb8aa3b, v56
	v_cndmask_b32_e32 v134, 0, v40, vcc
	v_cmp_le_i32_e32 vcc, v92, v60
	v_exp_f32_e32 v56, v56
	v_mul_f32_e32 v42, v42, v58
	v_cndmask_b32_e32 v135, 0, v41, vcc
	v_cmp_le_i32_e32 vcc, v92, v61
	v_or_b32_e32 v58, 3, v91
	v_or_b32_e32 v62, 16, v92
	v_cndmask_b32_e32 v142, 0, v42, vcc
	v_cmp_le_i32_e32 vcc, v92, v58
	v_add_f32_e32 v42, 0, v142
	v_add_f32_e32 v40, 0, v134
	v_cndmask_b32_e32 v143, 0, v43, vcc
	v_cmp_le_i32_e32 vcc, v62, v91
	v_add_f32_e32 v43, 0, v143
	v_add_f32_e32 v41, 0, v135
	v_cndmask_b32_e32 v144, 0, v28, vcc
	v_mul_f32_e32 v28, v29, v56
	v_sub_f32_e32 v29, v57, v50
	v_mul_f32_e32 v29, 0x3fb8aa3b, v29
	v_exp_f32_e32 v29, v29
	v_cmp_le_i32_e32 vcc, v62, v60
	v_add_f32_e32 v40, v144, v40
	v_add_u32_e32 v95, 0x1100, v79
	v_cndmask_b32_e32 v145, 0, v28, vcc
	v_sub_f32_e32 v28, v57, v51
	v_mul_f32_e32 v28, 0x3fb8aa3b, v28
	v_mul_f32_e32 v30, v30, v29
	v_exp_f32_e32 v56, v28
	ds_read2_b32 v[28:29], v76 offset0:32 offset1:48
	v_cmp_le_i32_e32 vcc, v62, v61
	v_add_f32_e32 v41, v145, v41
	v_mul_f32_e32 v31, v31, v56
	v_cndmask_b32_e32 v146, 0, v30, vcc
	v_add_f32_e32 v30, v146, v42
	s_waitcnt lgkmcnt(0)
	v_sub_f32_e32 v42, v28, v48
	v_mul_f32_e32 v42, 0x3fb8aa3b, v42
	v_exp_f32_e32 v42, v42
	v_cmp_le_i32_e32 vcc, v62, v58
	v_add_u32_e32 v96, 0x2200, v79
	v_add_u32_e32 v97, 0x3300, v79
	v_cndmask_b32_e32 v147, 0, v31, vcc
	v_add_f32_e32 v31, v147, v43
	v_or_b32_e32 v43, 32, v92
	v_mul_f32_e32 v32, v32, v42
	v_cmp_le_i32_e32 vcc, v43, v91
	v_sub_f32_e32 v42, v28, v49
	v_mul_f32_e32 v42, 0x3fb8aa3b, v42
	v_cndmask_b32_e32 v148, 0, v32, vcc
	v_add_f32_e32 v32, v148, v40
	v_sub_f32_e32 v40, v28, v50
	v_exp_f32_e32 v42, v42
	v_mul_f32_e32 v40, 0x3fb8aa3b, v40
	v_exp_f32_e32 v40, v40
	v_cmp_le_i32_e32 vcc, v43, v60
	v_mul_f32_e32 v33, v33, v42
	v_sub_f32_e32 v28, v28, v51
	v_cndmask_b32_e32 v149, 0, v33, vcc
	v_mul_f32_e32 v34, v34, v40
	v_cmp_le_i32_e32 vcc, v43, v61
	v_mul_f32_e32 v28, 0x3fb8aa3b, v28
	v_exp_f32_e32 v28, v28
	v_cndmask_b32_e32 v150, 0, v34, vcc
	v_sub_f32_e32 v34, v29, v48
	v_mul_f32_e32 v34, 0x3fb8aa3b, v34
	v_exp_f32_e32 v34, v34
	v_mul_f32_e32 v28, v35, v28
	v_cmp_le_i32_e32 vcc, v43, v58
	v_add_f32_e32 v30, v150, v30
	v_mul_f32_e32 v16, v16, v34
	v_sub_f32_e32 v34, v29, v49
	v_mul_f32_e32 v34, 0x3fb8aa3b, v34
	v_exp_f32_e32 v34, v34
	v_cndmask_b32_e32 v151, 0, v28, vcc
	v_add_f32_e32 v28, v151, v31
	v_or_b32_e32 v31, 48, v92
	v_cmp_le_i32_e32 vcc, v31, v91
	v_add_f32_e32 v33, v149, v41
	v_add_u32_e32 v172, v59, v95
	v_cndmask_b32_e32 v152, 0, v16, vcc
	v_mul_f32_e32 v16, v17, v34
	v_sub_f32_e32 v17, v29, v50
	v_mul_f32_e32 v17, 0x3fb8aa3b, v17
	v_exp_f32_e32 v17, v17
	v_cmp_le_i32_e32 vcc, v31, v60
	v_add_f32_e32 v32, v152, v32
	v_add_u32_e32 v173, v59, v96
	v_cndmask_b32_e32 v153, 0, v16, vcc
	v_sub_f32_e32 v16, v29, v51
	v_mul_f32_e32 v16, 0x3fb8aa3b, v16
	v_mul_f32_e32 v18, v18, v17
	v_exp_f32_e32 v29, v16
	ds_read2_b32 v[16:17], v76 offset0:64 offset1:80
	v_cmp_le_i32_e32 vcc, v31, v61
	v_add_f32_e32 v33, v153, v33
	v_mul_f32_e32 v19, v19, v29
	v_cndmask_b32_e32 v154, 0, v18, vcc
	s_waitcnt lgkmcnt(0)
	v_sub_f32_e32 v29, v16, v48
	v_add_f32_e32 v18, v154, v30
	v_mul_f32_e32 v29, 0x3fb8aa3b, v29
	v_sub_f32_e32 v30, v16, v49
	v_exp_f32_e32 v29, v29
	v_cmp_le_i32_e32 vcc, v31, v58
	v_mul_f32_e32 v30, 0x3fb8aa3b, v30
	v_sub_f32_e32 v31, v16, v50
	v_exp_f32_e32 v30, v30
	v_mul_f32_e32 v31, 0x3fb8aa3b, v31
	v_cndmask_b32_e32 v155, 0, v19, vcc
	v_exp_f32_e32 v31, v31
	v_add_f32_e32 v19, v155, v28
	v_or_b32_e32 v28, 64, v92
	v_mul_f32_e32 v29, v36, v29
	v_cmp_le_i32_e32 vcc, v28, v91
	v_mul_f32_e32 v30, v37, v30
	v_mul_f32_e32 v31, v38, v31
	v_cndmask_b32_e32 v156, 0, v29, vcc
	v_cmp_le_i32_e32 vcc, v28, v60
	v_sub_f32_e32 v16, v16, v51
	v_mul_f32_e32 v16, 0x3fb8aa3b, v16
	v_cndmask_b32_e32 v157, 0, v30, vcc
	v_cmp_le_i32_e32 vcc, v28, v61
	v_exp_f32_e32 v16, v16
	v_add_f32_e32 v29, v156, v32
	v_cndmask_b32_e32 v158, 0, v31, vcc
	v_sub_f32_e32 v31, v17, v48
	v_mul_f32_e32 v31, 0x3fb8aa3b, v31
	v_exp_f32_e32 v31, v31
	v_mul_f32_e32 v16, v39, v16
	v_cmp_le_i32_e32 vcc, v28, v58
	v_or_b32_e32 v28, 0x50, v92
	v_add_f32_e32 v30, v157, v33
	v_cndmask_b32_e32 v159, 0, v16, vcc
	v_mul_f32_e32 v16, v20, v31
	v_sub_f32_e32 v20, v17, v49
	v_mul_f32_e32 v20, 0x3fb8aa3b, v20
	v_exp_f32_e32 v20, v20
	v_cmp_le_i32_e32 vcc, v28, v91
	v_add_f32_e32 v19, v159, v19
	v_add_f32_e32 v18, v158, v18
	v_cndmask_b32_e32 v160, 0, v16, vcc
	v_mul_f32_e32 v16, v21, v20
	v_sub_f32_e32 v20, v17, v50
	v_mul_f32_e32 v20, 0x3fb8aa3b, v20
	v_exp_f32_e32 v20, v20
	v_cmp_le_i32_e32 vcc, v28, v60
	v_add_f32_e32 v29, v160, v29
	v_add_u32_e32 v174, v59, v97
	v_cndmask_b32_e32 v161, 0, v16, vcc
	v_sub_f32_e32 v16, v17, v51
	v_mul_f32_e32 v16, 0x3fb8aa3b, v16
	v_mul_f32_e32 v20, v22, v20
	v_exp_f32_e32 v22, v16
	ds_read2_b32 v[16:17], v76 offset0:96 offset1:112
	v_cmp_le_i32_e32 vcc, v28, v61
	v_add_f32_e32 v21, v161, v30
	s_nop 0
	v_cndmask_b32_e32 v162, 0, v20, vcc
	v_mul_f32_e32 v20, v23, v22
	s_waitcnt lgkmcnt(0)
	v_sub_f32_e32 v22, v16, v48
	v_mul_f32_e32 v22, 0x3fb8aa3b, v22
	v_sub_f32_e32 v23, v16, v49
	v_exp_f32_e32 v22, v22
	v_cmp_le_i32_e32 vcc, v28, v58
	v_mul_f32_e32 v23, 0x3fb8aa3b, v23
	v_sub_f32_e32 v28, v16, v50
	v_exp_f32_e32 v23, v23
	v_mul_f32_e32 v28, 0x3fb8aa3b, v28
	v_exp_f32_e32 v28, v28
	v_cndmask_b32_e32 v163, 0, v20, vcc
	v_or_b32_e32 v20, 0x60, v92
	v_mul_f32_e32 v22, v44, v22
	v_cmp_le_i32_e32 vcc, v20, v91
	v_mul_f32_e32 v23, v45, v23
	v_sub_f32_e32 v16, v16, v51
	v_cndmask_b32_e32 v164, 0, v22, vcc
	v_cmp_le_i32_e32 vcc, v20, v60
	v_mul_f32_e32 v16, 0x3fb8aa3b, v16
	v_exp_f32_e32 v16, v16
	v_cndmask_b32_e32 v165, 0, v23, vcc
	v_mul_f32_e32 v23, v46, v28
	v_cmp_le_i32_e32 vcc, v20, v61
	v_mul_f32_e32 v16, v47, v16
	v_add_f32_e32 v19, v163, v19
	v_cndmask_b32_e32 v166, 0, v23, vcc
	v_sub_f32_e32 v23, v17, v48
	v_mul_f32_e32 v23, 0x3fb8aa3b, v23
	v_exp_f32_e32 v23, v23
	v_cmp_le_i32_e32 vcc, v20, v58
	v_add_f32_e32 v22, v164, v29
	v_add_f32_e32 v18, v162, v18
	v_mul_f32_e32 v20, v24, v23
	v_sub_f32_e32 v23, v17, v49
	v_mul_f32_e32 v23, 0x3fb8aa3b, v23
	v_cndmask_b32_e32 v167, 0, v16, vcc
	v_exp_f32_e32 v23, v23
	v_add_f32_e32 v16, v167, v19
	v_or_b32_e32 v19, 0x70, v92
	v_cmp_le_i32_e32 vcc, v19, v91
	v_add_f32_e32 v21, v165, v21
	v_add_f32_e32 v18, v166, v18
	v_cndmask_b32_e32 v168, 0, v20, vcc
	v_add_f32_e32 v20, v168, v22
	v_mul_f32_e32 v22, v25, v23
	v_sub_f32_e32 v23, v17, v50
	v_mul_f32_e32 v23, 0x3fb8aa3b, v23
	v_exp_f32_e32 v23, v23
	v_cmp_le_i32_e32 vcc, v19, v60
	v_sub_f32_e32 v17, v17, v51
	v_mul_f32_e32 v17, 0x3fb8aa3b, v17
	v_cndmask_b32_e32 v169, 0, v22, vcc
	v_mul_f32_e32 v22, v26, v23
	ds_bpermute_b32 v23, v82, v20
	v_cmp_le_i32_e32 vcc, v19, v61
	v_exp_f32_e32 v17, v17
	v_add_f32_e32 v21, v169, v21
	v_cndmask_b32_e32 v170, 0, v22, vcc
	s_waitcnt lgkmcnt(0)
	v_add_f32_e32 v20, v20, v23
	ds_bpermute_b32 v22, v83, v20
	v_add_f32_e32 v18, v170, v18
	v_mul_f32_e32 v17, v27, v17
	v_cmp_le_i32_e32 vcc, v19, v58
	ds_bpermute_b32 v19, v82, v18
	s_waitcnt lgkmcnt(1)
	v_add_f32_e32 v20, v20, v22
	ds_bpermute_b32 v22, v84, v20
	v_cndmask_b32_e32 v171, 0, v17, vcc
	ds_bpermute_b32 v17, v82, v21
	v_add_f32_e32 v16, v171, v16
	s_waitcnt lgkmcnt(2)
	v_add_f32_e32 v18, v18, v19
	s_waitcnt lgkmcnt(1)
	v_add_f32_e32 v102, v20, v22
	ds_bpermute_b32 v20, v82, v16
	s_waitcnt lgkmcnt(1)
	v_add_f32_e32 v17, v21, v17
	ds_bpermute_b32 v21, v83, v17
	ds_bpermute_b32 v19, v83, v18
	ds_read_b128 v[24:27], v173
	s_waitcnt lgkmcnt(3)
	v_add_f32_e32 v16, v16, v20
	ds_bpermute_b32 v20, v83, v16
	s_waitcnt lgkmcnt(3)
	v_add_f32_e32 v17, v17, v21
	s_waitcnt lgkmcnt(2)
	v_add_f32_e32 v18, v18, v19
	ds_bpermute_b32 v21, v84, v17
	ds_bpermute_b32 v19, v84, v18
	s_waitcnt lgkmcnt(2)
	v_add_f32_e32 v32, v16, v20
	ds_bpermute_b32 v33, v84, v32
	ds_read_b128 v[28:31], v174
	s_waitcnt lgkmcnt(3)
	v_add_f32_e32 v104, v17, v21
	s_waitcnt lgkmcnt(2)
	v_add_f32_e32 v106, v18, v19
	ds_read_b128 v[16:19], v172
	s_waitcnt lgkmcnt(2)
	v_add_f32_e32 v108, v32, v33
	ds_bpermute_b32 v103, v85, v102
	ds_bpermute_b32 v105, v85, v104
	ds_bpermute_b32 v107, v85, v106
	ds_bpermute_b32 v109, v85, v108
	v_mfma_f32_16x16x32_bf16 v[20:23], v[12:15], v[52:55], 0
	s_waitcnt lgkmcnt(4)
	v_mfma_f32_16x16x32_bf16 v[16:19], v[12:15], v[16:19], 0
	v_mfma_f32_16x16x32_bf16 v[24:27], v[12:15], v[24:27], 0
	v_mfma_f32_16x16x32_bf16 v[28:31], v[12:15], v[28:31], 0
	v_add_u32_e32 v98, 0x4400, v79
	v_add_u32_e32 v99, 0x5500, v79
	v_add_u32_e32 v100, 0x6600, v79
	v_add_u32_e32 v101, 0x7700, v79
	v_add_u32_e32 v175, v59, v98
	v_add_u32_e32 v176, v59, v99
	v_add_u32_e32 v177, v59, v100
	v_add_u32_e32 v178, v59, v101
	ds_read_b128 v[32:35], v175
	ds_read_b128 v[36:39], v176
	ds_read_b128 v[40:43], v177
	ds_read_b128 v[44:47], v178
	s_waitcnt lgkmcnt(3)
	v_mfma_f32_16x16x32_bf16 v[32:35], v[12:15], v[32:35], 0
	s_waitcnt lgkmcnt(2)
	v_mfma_f32_16x16x32_bf16 v[36:39], v[12:15], v[36:39], 0
	s_waitcnt lgkmcnt(1)
	v_mfma_f32_16x16x32_bf16 v[40:43], v[12:15], v[40:43], 0
	s_waitcnt lgkmcnt(0)
	v_mfma_f32_16x16x32_bf16 v[44:47], v[12:15], v[44:47], 0
	ds_read_b128 v[48:51], v93 offset:34816
	ds_read_b128 v[52:55], v93 offset:39168
	ds_read_b128 v[56:59], v93 offset:43520
	ds_read_b128 v[60:63], v93 offset:47872
	s_waitcnt lgkmcnt(3)
	v_mfma_f32_16x16x32_bf16 v[48:51], v[12:15], v[48:51], 0
	s_waitcnt lgkmcnt(2)
	v_mfma_f32_16x16x32_bf16 v[52:55], v[12:15], v[52:55], 0
	s_waitcnt lgkmcnt(1)
	v_mfma_f32_16x16x32_bf16 v[56:59], v[12:15], v[56:59], 0
	s_waitcnt lgkmcnt(0)
	v_mfma_f32_16x16x32_bf16 v[60:63], v[12:15], v[60:63], 0
	ds_read_b128 v[64:67], v93 offset:52224
	ds_read_b128 v[68:71], v93 offset:56576
	ds_read_b128 v[72:75], v93 offset:60928
	ds_read_b128 v[110:113], v93 offset:65280
	s_waitcnt lgkmcnt(3)
	v_mfma_f32_16x16x32_bf16 v[64:67], v[12:15], v[64:67], 0
	s_waitcnt lgkmcnt(2)
	v_mfma_f32_16x16x32_bf16 v[68:71], v[12:15], v[68:71], 0
	s_waitcnt lgkmcnt(1)
	v_mfma_f32_16x16x32_bf16 v[72:75], v[12:15], v[72:75], 0
	s_waitcnt lgkmcnt(0)
	v_mfma_f32_16x16x32_bf16 v[12:15], v[12:15], v[110:113], 0
	ds_read_b128 v[110:113], v93 offset:64
	ds_read_b128 v[114:117], v172 offset:64
	s_waitcnt lgkmcnt(1)
	v_mfma_f32_16x16x32_bf16 v[20:23], v[8:11], v[110:113], v[20:23]
	s_waitcnt lgkmcnt(0)
	v_mfma_f32_16x16x32_bf16 v[16:19], v[8:11], v[114:117], v[16:19]
	ds_read_b128 v[110:113], v173 offset:64
	ds_read_b128 v[114:117], v174 offset:64
	s_waitcnt lgkmcnt(1)
	v_mfma_f32_16x16x32_bf16 v[24:27], v[8:11], v[110:113], v[24:27]
	s_waitcnt lgkmcnt(0)
	v_mfma_f32_16x16x32_bf16 v[28:31], v[8:11], v[114:117], v[28:31]
	ds_read_b128 v[110:113], v175 offset:64
	ds_read_b128 v[114:117], v176 offset:64
	s_waitcnt lgkmcnt(1)
	v_mfma_f32_16x16x32_bf16 v[32:35], v[8:11], v[110:113], v[32:35]
	s_waitcnt lgkmcnt(0)
	v_mfma_f32_16x16x32_bf16 v[36:39], v[8:11], v[114:117], v[36:39]
	ds_read_b128 v[110:113], v177 offset:64
	ds_read_b128 v[114:117], v178 offset:64
	s_waitcnt lgkmcnt(1)
	v_mfma_f32_16x16x32_bf16 v[40:43], v[8:11], v[110:113], v[40:43]
	s_waitcnt lgkmcnt(0)
	v_mfma_f32_16x16x32_bf16 v[44:47], v[8:11], v[114:117], v[44:47]
	ds_read_b128 v[110:113], v93 offset:34880
	ds_read_b128 v[114:117], v93 offset:39232
	s_waitcnt lgkmcnt(1)
	v_mfma_f32_16x16x32_bf16 v[48:51], v[8:11], v[110:113], v[48:51]
	s_waitcnt lgkmcnt(0)
	v_mfma_f32_16x16x32_bf16 v[52:55], v[8:11], v[114:117], v[52:55]
	ds_read_b128 v[110:113], v93 offset:43584
	ds_read_b128 v[114:117], v93 offset:47936
	s_waitcnt lgkmcnt(1)
	v_mfma_f32_16x16x32_bf16 v[56:59], v[8:11], v[110:113], v[56:59]
	s_waitcnt lgkmcnt(0)
	v_mfma_f32_16x16x32_bf16 v[60:63], v[8:11], v[114:117], v[60:63]
	ds_read_b128 v[110:113], v93 offset:52288
	ds_read_b128 v[114:117], v93 offset:56640
	s_waitcnt lgkmcnt(1)
	v_mfma_f32_16x16x32_bf16 v[64:67], v[8:11], v[110:113], v[64:67]
	s_waitcnt lgkmcnt(0)
	v_mfma_f32_16x16x32_bf16 v[68:71], v[8:11], v[114:117], v[68:71]
	ds_read_b128 v[110:113], v93 offset:60992
	ds_read_b128 v[114:117], v93 offset:65344
	s_waitcnt lgkmcnt(1)
	v_mfma_f32_16x16x32_bf16 v[72:75], v[8:11], v[110:113], v[72:75]
	s_waitcnt lgkmcnt(0)
	v_mfma_f32_16x16x32_bf16 v[8:11], v[8:11], v[114:117], v[12:15]
	s_nop 2
	ds_read_b128 v[12:15], v93 offset:128
	ds_read_b128 v[110:113], v172 offset:128
	s_waitcnt lgkmcnt(1)
	v_mfma_f32_16x16x32_bf16 v[12:15], v[4:7], v[12:15], v[20:23]
	s_waitcnt lgkmcnt(0)
	v_mfma_f32_16x16x32_bf16 v[16:19], v[4:7], v[110:113], v[16:19]
	s_nop 0
	ds_read_b128 v[20:23], v173 offset:128
	ds_read_b128 v[110:113], v174 offset:128
	s_waitcnt lgkmcnt(1)
	v_mfma_f32_16x16x32_bf16 v[20:23], v[4:7], v[20:23], v[24:27]
	s_waitcnt lgkmcnt(0)
	v_mfma_f32_16x16x32_bf16 v[24:27], v[4:7], v[110:113], v[28:31]
	s_nop 2
	ds_read_b128 v[28:31], v175 offset:128
	ds_read_b128 v[110:113], v176 offset:128
	s_waitcnt lgkmcnt(1)
	v_mfma_f32_16x16x32_bf16 v[28:31], v[4:7], v[28:31], v[32:35]
	s_waitcnt lgkmcnt(0)
	v_mfma_f32_16x16x32_bf16 v[32:35], v[4:7], v[110:113], v[36:39]
	s_nop 2
	ds_read_b128 v[36:39], v177 offset:128
	ds_read_b128 v[110:113], v178 offset:128
	s_waitcnt lgkmcnt(1)
	v_mfma_f32_16x16x32_bf16 v[36:39], v[4:7], v[36:39], v[40:43]
	s_waitcnt lgkmcnt(0)
	v_mfma_f32_16x16x32_bf16 v[110:113], v[4:7], v[110:113], v[44:47]
	s_nop 0
	ds_read_b128 v[40:43], v93 offset:34944
	s_nop 0
	ds_read_b128 v[44:47], v93 offset:39296
	s_waitcnt lgkmcnt(1)
	v_mfma_f32_16x16x32_bf16 v[114:117], v[4:7], v[40:43], v[48:51]
	s_waitcnt lgkmcnt(0)
	v_mfma_f32_16x16x32_bf16 v[118:121], v[4:7], v[44:47], v[52:55]
	ds_read_b128 v[40:43], v93 offset:43648
	ds_read_b128 v[44:47], v93 offset:48000
	s_waitcnt lgkmcnt(1)
	v_mfma_f32_16x16x32_bf16 v[122:125], v[4:7], v[40:43], v[56:59]
	s_waitcnt lgkmcnt(0)
	v_mfma_f32_16x16x32_bf16 v[126:129], v[4:7], v[44:47], v[60:63]
	ds_read_b128 v[40:43], v93 offset:52352
	ds_read_b128 v[44:47], v93 offset:56704
	s_waitcnt lgkmcnt(1)
	v_mfma_f32_16x16x32_bf16 v[130:133], v[4:7], v[40:43], v[64:67]
	s_waitcnt lgkmcnt(0)
	v_mfma_f32_16x16x32_bf16 v[68:71], v[4:7], v[44:47], v[68:71]
	ds_read_b128 v[40:43], v93 offset:61056
	ds_read_b128 v[44:47], v93 offset:65408
	s_waitcnt lgkmcnt(1)
	v_mfma_f32_16x16x32_bf16 v[72:75], v[4:7], v[40:43], v[72:75]
	s_waitcnt lgkmcnt(0)
	v_mfma_f32_16x16x32_bf16 v[138:141], v[4:7], v[44:47], v[8:11]
	ds_read_b128 v[4:7], v93 offset:192
	s_nop 1
	ds_read_b128 v[8:11], v172 offset:192
	s_waitcnt lgkmcnt(1)
	v_mfma_f32_16x16x32_bf16 v[64:67], v[0:3], v[4:7], v[12:15]
	s_waitcnt lgkmcnt(0)
	v_mfma_f32_16x16x32_bf16 v[60:63], v[0:3], v[8:11], v[16:19]
	ds_read_b128 v[4:7], v173 offset:192
	ds_read_b128 v[8:11], v174 offset:192
	s_waitcnt lgkmcnt(1)
	v_mfma_f32_16x16x32_bf16 v[56:59], v[0:3], v[4:7], v[20:23]
	s_waitcnt lgkmcnt(0)
	v_mfma_f32_16x16x32_bf16 v[52:55], v[0:3], v[8:11], v[24:27]
	ds_read_b128 v[4:7], v175 offset:192
	ds_read_b128 v[8:11], v176 offset:192
	s_waitcnt lgkmcnt(1)
	v_mfma_f32_16x16x32_bf16 v[48:51], v[0:3], v[4:7], v[28:31]
	s_waitcnt lgkmcnt(0)
	v_mfma_f32_16x16x32_bf16 v[44:47], v[0:3], v[8:11], v[32:35]
	ds_read_b128 v[4:7], v177 offset:192
	ds_read_b128 v[8:11], v178 offset:192
	s_waitcnt lgkmcnt(1)
	v_mfma_f32_16x16x32_bf16 v[40:43], v[0:3], v[4:7], v[36:39]
	s_waitcnt lgkmcnt(0)
	v_mfma_f32_16x16x32_bf16 v[36:39], v[0:3], v[8:11], v[110:113]
	ds_read_b128 v[4:7], v93 offset:35008
	ds_read_b128 v[8:11], v93 offset:39360
	s_waitcnt lgkmcnt(1)
	v_mfma_f32_16x16x32_bf16 v[32:35], v[0:3], v[4:7], v[114:117]
	s_waitcnt lgkmcnt(0)
	v_mfma_f32_16x16x32_bf16 v[16:19], v[0:3], v[8:11], v[118:121]
	ds_read_b128 v[4:7], v93 offset:43712
	ds_read_b128 v[8:11], v93 offset:48064
	s_waitcnt lgkmcnt(1)
	v_mfma_f32_16x16x32_bf16 v[28:31], v[0:3], v[4:7], v[122:125]
	s_waitcnt lgkmcnt(0)
	v_mfma_f32_16x16x32_bf16 v[20:23], v[0:3], v[8:11], v[126:129]
	ds_read_b128 v[4:7], v93 offset:52416
	ds_read_b128 v[8:11], v93 offset:56768
	s_waitcnt lgkmcnt(1)
	v_mfma_f32_16x16x32_bf16 v[24:27], v[0:3], v[4:7], v[130:133]
	ds_read_b128 v[4:7], v93 offset:61120
	ds_read_b128 v[12:15], v93 offset:65472
	s_waitcnt lgkmcnt(2)
	v_mfma_f32_16x16x32_bf16 v[8:11], v[0:3], v[8:11], v[68:71]
	s_waitcnt lgkmcnt(1)
	v_mfma_f32_16x16x32_bf16 v[4:7], v[0:3], v[4:7], v[72:75]
	s_waitcnt lgkmcnt(0)
	v_mfma_f32_16x16x32_bf16 v[0:3], v[0:3], v[12:15], v[138:141]
	ds_read_b128 v[68:71], v94 offset:2048
	ds_read_b128 v[72:75], v94 offset:1536
	ds_read_b128 v[12:15], v94 offset:1024
	v_lshlrev_b32_e32 v92, 1, v92
	v_bfe_u32 v94, v134, 16, 1
	v_mul_lo_u32 v110, v91, s81
	v_add3_u32 v94, v134, v94, s87
	v_add3_u32 v92, 0, v92, v110
	s_waitcnt lgkmcnt(0)
	s_barrier
	ds_write_b16_d16_hi v92, v94 offset:38912
	v_bfe_u32 v94, v135, 16, 1
	v_add3_u32 v94, v135, v94, s87
	ds_write_b16_d16_hi v92, v94 offset:39184
	v_bfe_u32 v94, v142, 16, 1
	v_add3_u32 v94, v142, v94, s87
	ds_write_b16_d16_hi v92, v94 offset:39456
	v_bfe_u32 v94, v143, 16, 1
	v_add3_u32 v94, v143, v94, s87
	ds_write_b16_d16_hi v92, v94 offset:39728
	v_bfe_u32 v94, v144, 16, 1
	v_add3_u32 v94, v144, v94, s87
	ds_write_b16_d16_hi v92, v94 offset:38944
	v_bfe_u32 v94, v145, 16, 1
	v_add3_u32 v94, v145, v94, s87
	ds_write_b16_d16_hi v92, v94 offset:39216
	v_bfe_u32 v94, v146, 16, 1
	v_add3_u32 v94, v146, v94, s87
	ds_write_b16_d16_hi v92, v94 offset:39488
	v_bfe_u32 v94, v147, 16, 1
	v_add3_u32 v94, v147, v94, s87
	ds_write_b16_d16_hi v92, v94 offset:39760
	v_bfe_u32 v94, v148, 16, 1
	v_add3_u32 v94, v148, v94, s87
	ds_write_b16_d16_hi v92, v94 offset:38976
	v_bfe_u32 v94, v149, 16, 1
	v_add3_u32 v94, v149, v94, s87
	ds_write_b16_d16_hi v92, v94 offset:39248
	v_bfe_u32 v94, v150, 16, 1
	v_add3_u32 v94, v150, v94, s87
	ds_write_b16_d16_hi v92, v94 offset:39520
	v_bfe_u32 v94, v151, 16, 1
	v_add3_u32 v94, v151, v94, s87
	ds_write_b16_d16_hi v92, v94 offset:39792
	v_bfe_u32 v94, v152, 16, 1
	v_add3_u32 v94, v152, v94, s87
	ds_write_b16_d16_hi v92, v94 offset:39008
	v_bfe_u32 v94, v153, 16, 1
	v_add3_u32 v94, v153, v94, s87
	ds_write_b16_d16_hi v92, v94 offset:39280
	v_bfe_u32 v94, v154, 16, 1
	v_add3_u32 v94, v154, v94, s87
	ds_write_b16_d16_hi v92, v94 offset:39552
	v_bfe_u32 v94, v155, 16, 1
	v_add3_u32 v94, v155, v94, s87
	ds_write_b16_d16_hi v92, v94 offset:39824
	v_bfe_u32 v94, v156, 16, 1
	v_add3_u32 v94, v156, v94, s87
	ds_write_b16_d16_hi v92, v94 offset:39040
	v_bfe_u32 v94, v157, 16, 1
	v_add3_u32 v94, v157, v94, s87
	ds_write_b16_d16_hi v92, v94 offset:39312
	v_bfe_u32 v94, v158, 16, 1
	v_add3_u32 v94, v158, v94, s87
	ds_write_b16_d16_hi v92, v94 offset:39584
	v_bfe_u32 v94, v159, 16, 1
	v_add3_u32 v94, v159, v94, s87
	ds_write_b16_d16_hi v92, v94 offset:39856
	v_bfe_u32 v94, v160, 16, 1
	v_add3_u32 v94, v160, v94, s87
	ds_write_b16_d16_hi v92, v94 offset:39072
	v_bfe_u32 v94, v161, 16, 1
	v_add3_u32 v94, v161, v94, s87
	ds_write_b16_d16_hi v92, v94 offset:39344
	v_bfe_u32 v94, v162, 16, 1
	v_add3_u32 v94, v162, v94, s87
	ds_write_b16_d16_hi v92, v94 offset:39616
	v_bfe_u32 v94, v163, 16, 1
	v_add3_u32 v94, v163, v94, s87
	ds_write_b16_d16_hi v92, v94 offset:39888
	v_bfe_u32 v94, v164, 16, 1
	v_add3_u32 v94, v164, v94, s87
	ds_write_b16_d16_hi v92, v94 offset:39104
	v_bfe_u32 v94, v165, 16, 1
	v_add3_u32 v94, v165, v94, s87
	ds_write_b16_d16_hi v92, v94 offset:39376
	v_bfe_u32 v94, v166, 16, 1
	v_add3_u32 v94, v166, v94, s87
	ds_write_b16_d16_hi v92, v94 offset:39648
	v_bfe_u32 v94, v167, 16, 1
	v_add3_u32 v94, v167, v94, s87
	ds_write_b16_d16_hi v92, v94 offset:39920
	v_bfe_u32 v94, v168, 16, 1
	v_add3_u32 v94, v168, v94, s87
	ds_write_b16_d16_hi v92, v94 offset:39136
	v_bfe_u32 v94, v169, 16, 1
	v_add3_u32 v94, v169, v94, s87
	ds_write_b16_d16_hi v92, v94 offset:39408
	v_bfe_u32 v94, v170, 16, 1
	v_add3_u32 v94, v170, v94, s87
	ds_write_b16_d16_hi v92, v94 offset:39680
	v_bfe_u32 v94, v171, 16, 1
	v_add3_u32 v94, v171, v94, s87
	ds_write_b16_d16_hi v92, v94 offset:39952
	s_and_saveexec_b64 s[4:5], s[2:3]
	s_cbranch_execz .LBB0_949
	v_and_b32_e32 v212, 0x7f, v78
	v_ashrrev_i32_e32 v213, 7, v78
	v_mul_u32_u24_e32 v215, 0x880, v213
	v_lshl_add_u32 v215, v212, 1, v215
	v_add_u32_e32 v215, s84, v215
	ds_write_b16 v215, v180 offset:0
	ds_write_b16_d16_hi v215, v180 offset:272
	ds_write_b16 v215, v181 offset:544
	ds_write_b16_d16_hi v215, v181 offset:816
	ds_write_b16 v215, v182 offset:1088
	ds_write_b16_d16_hi v215, v182 offset:1360
	ds_write_b16 v215, v183 offset:1632
	ds_write_b16_d16_hi v215, v183 offset:1904
	ds_write_b16 v215, v184 offset:8704
	ds_write_b16_d16_hi v215, v184 offset:8976
	ds_write_b16 v215, v185 offset:9248
	ds_write_b16_d16_hi v215, v185 offset:9520
	ds_write_b16 v215, v186 offset:9792
	ds_write_b16_d16_hi v215, v186 offset:10064
	ds_write_b16 v215, v187 offset:10336
	ds_write_b16_d16_hi v215, v187 offset:10608
	ds_write_b16 v215, v188 offset:17408
	ds_write_b16_d16_hi v215, v188 offset:17680
	ds_write_b16 v215, v189 offset:17952
	ds_write_b16_d16_hi v215, v189 offset:18224
	ds_write_b16 v215, v190 offset:18496
	ds_write_b16_d16_hi v215, v190 offset:18768
	ds_write_b16 v215, v191 offset:19040
	ds_write_b16_d16_hi v215, v191 offset:19312
	ds_write_b16 v215, v192 offset:26112
	ds_write_b16_d16_hi v215, v192 offset:26384
	ds_write_b16 v215, v193 offset:26656
	ds_write_b16_d16_hi v215, v193 offset:26928
	ds_write_b16 v215, v194 offset:27200
	ds_write_b16_d16_hi v215, v194 offset:27472
	ds_write_b16 v215, v195 offset:27744
	ds_write_b16_d16_hi v215, v195 offset:28016
	ds_write_b16 v215, v196 offset:34816
	ds_write_b16_d16_hi v215, v196 offset:35088
	ds_write_b16 v215, v197 offset:35360
	ds_write_b16_d16_hi v215, v197 offset:35632
	ds_write_b16 v215, v198 offset:35904
	ds_write_b16_d16_hi v215, v198 offset:36176
	ds_write_b16 v215, v199 offset:36448
	ds_write_b16_d16_hi v215, v199 offset:36720
	ds_write_b16 v215, v200 offset:43520
	ds_write_b16_d16_hi v215, v200 offset:43792
	ds_write_b16 v215, v201 offset:44064
	ds_write_b16_d16_hi v215, v201 offset:44336
	ds_write_b16 v215, v202 offset:44608
	ds_write_b16_d16_hi v215, v202 offset:44880
	ds_write_b16 v215, v203 offset:45152
	ds_write_b16_d16_hi v215, v203 offset:45424
	ds_write_b16 v215, v204 offset:52224
	ds_write_b16_d16_hi v215, v204 offset:52496
	ds_write_b16 v215, v205 offset:52768
	ds_write_b16_d16_hi v215, v205 offset:53040
	ds_write_b16 v215, v206 offset:53312
	ds_write_b16_d16_hi v215, v206 offset:53584
	ds_write_b16 v215, v207 offset:53856
	ds_write_b16_d16_hi v215, v207 offset:54128
	ds_write_b16 v215, v208 offset:60928
	ds_write_b16_d16_hi v215, v208 offset:61200
	ds_write_b16 v215, v209 offset:61472
	ds_write_b16_d16_hi v215, v209 offset:61744
	ds_write_b16 v215, v210 offset:62016
	ds_write_b16_d16_hi v215, v210 offset:62288
	ds_write_b16 v215, v211 offset:62560
	ds_write_b16_d16_hi v215, v211 offset:62832
